# speedup vs baseline: 1.1027x; 1.0018x over previous
; DEV void scan_phase(const Params& p, char* smem, const float* __restrict__ nx, const float* __restrict__ ng, u16* __restrict__ nh) {
;     ...
;           } else if ((c & 3) == 1) {
;             float ss = 0.f;
; #pragma unroll
;             for (int i = 0; i < 4; ++i) ss += nv[i].x * nv[i].x + nv[i].y * nv[i].y + nv[i].z * nv[i].z + nv[i].w * nv[i].w;
;             ss = wave_sum(ss);
;             const float rs = rsqrtf(ss * (1.f / 1024.f) + 1e-6f);
; #pragma unroll
;             for (int i = 0; i < 4; ++i) {
;               const float4 g4 = ((const float4*)ng)[lane + 64 * i];
;               uint2 o;
;               o.x = pack2bf(nv[i].x * rs * g4.x, nv[i].y * rs * g4.y);
;               o.y = pack2bf(nv[i].z * rs * g4.z, nv[i].w * rs * g4.w);
;               *(uint2*)(nh + (long)nrow * 1024 + (lane + 64 * i) * 4) = o;
;             }
;           }
.LBB0_645:
	s_and_b32 s40, s31, 1
	s_and_saveexec_b64 s[44:45], s[10:11]
	s_xor_b64 s[90:91], exec, s[44:45]
	s_cbranch_execz .LBB0_657
	s_andn2_b64 vcc, exec, s[36:37]
	s_cbranch_vccnz .LBB0_653
	s_and_b32 s41, s31, 3
	s_waitcnt lgkmcnt(6)
	v_and_or_b32 v40, s31, 60, v89
	s_cmp_lt_i32 s41, 1
	s_mov_b64 s[44:45], -1
	s_cbranch_scc1 .LBB0_651
	s_cmp_lg_u32 s41, 1
	s_cbranch_scc1 .LBB0_650
	s_waitcnt vmcnt(2)
	v_mov_b32_e32 v42, v28
	v_mov_b32_e32 v43, v24
	v_pk_mul_f32 v[42:43], v[42:43], v[42:43]
	s_waitcnt lgkmcnt(5)
	v_mov_b32_e32 v44, v29
	v_mov_b32_e32 v45, v25
	v_pk_fma_f32 v[42:43], v[44:45], v[44:45], v[42:43]
	v_mov_b32_e32 v44, v30
	v_mov_b32_e32 v45, v26
	v_pk_fma_f32 v[42:43], v[44:45], v[44:45], v[42:43]
	v_mov_b32_e32 v44, v31
	v_mov_b32_e32 v45, v27
	v_pk_fma_f32 v[42:43], v[44:45], v[44:45], v[42:43]
	s_waitcnt vmcnt(0)
	v_mov_b32_e32 v44, v36
	v_mov_b32_e32 v45, v32
	v_pk_mul_f32 v[44:45], v[44:45], v[44:45]
	v_mov_b32_e32 v46, v37
	v_mov_b32_e32 v47, v33
	v_pk_fma_f32 v[44:45], v[46:47], v[46:47], v[44:45]
	v_mov_b32_e32 v46, v38
	v_mov_b32_e32 v47, v34
	v_pk_fma_f32 v[44:45], v[46:47], v[46:47], v[44:45]
	v_mov_b32_e32 v46, v39
	v_mov_b32_e32 v47, v35
	v_pk_fma_f32 v[44:45], v[46:47], v[46:47], v[44:45]
	s_waitcnt lgkmcnt(2)
	global_load_dwordx4 v[46:49], v[78:79], off
	global_load_dwordx4 v[144:147], v[78:79], off offset:1024
	global_load_dwordx4 v[148:151], v[78:79], off offset:2048
	global_load_dwordx4 v[152:155], v[78:79], off offset:3072
	v_add_f32_e32 v41, v42, v43
	v_and_b32_e32 v42, 64, v199
	v_add_u32_e32 v42, 64, v42
	v_xor_b32_e32 v43, 32, v199
	v_cmp_lt_i32_e32 vcc, v43, v42
	v_add_f32_e32 v41, v45, v41
	v_add_f32_e32 v41, v44, v41
	v_cndmask_b32_e32 v43, v199, v43, vcc
	v_lshlrev_b32_e32 v43, 2, v43
	ds_bpermute_b32 v43, v43, v41
	v_mov_b32_e32 v91, v141
	v_mov_b32_e32 v93, v141
	v_mov_b32_e32 v95, v141
	s_waitcnt lgkmcnt(0)
	v_add_f32_e32 v41, v41, v43
	v_xor_b32_e32 v43, 16, v199
	v_cmp_lt_i32_e32 vcc, v43, v42
	s_nop 1
	v_cndmask_b32_e32 v43, v199, v43, vcc
	v_lshlrev_b32_e32 v43, 2, v43
	ds_bpermute_b32 v43, v43, v41
	s_waitcnt lgkmcnt(0)
	v_add_f32_e32 v41, v41, v43
	v_xor_b32_e32 v43, 8, v199
	v_cmp_lt_i32_e32 vcc, v43, v42
	s_nop 1
	v_cndmask_b32_e32 v43, v199, v43, vcc
	v_lshlrev_b32_e32 v43, 2, v43
	ds_bpermute_b32 v43, v43, v41
	s_waitcnt lgkmcnt(0)
	v_add_f32_e32 v41, v41, v43
	v_xor_b32_e32 v43, 4, v199
	v_cmp_lt_i32_e32 vcc, v43, v42
	s_nop 1
	v_cndmask_b32_e32 v43, v199, v43, vcc
	v_lshlrev_b32_e32 v43, 2, v43
	ds_bpermute_b32 v43, v43, v41
	s_waitcnt lgkmcnt(0)
	v_add_f32_e32 v41, v41, v43
	v_xor_b32_e32 v43, 2, v199
	v_cmp_lt_i32_e32 vcc, v43, v42
	s_nop 1
	v_cndmask_b32_e32 v43, v199, v43, vcc
	v_lshlrev_b32_e32 v43, 2, v43
	ds_bpermute_b32 v43, v43, v41
	s_waitcnt lgkmcnt(0)
	v_add_f32_e32 v41, v41, v43
	v_xor_b32_e32 v43, 1, v199
	v_cmp_lt_i32_e32 vcc, v43, v42
	s_nop 1
	v_cndmask_b32_e32 v42, v199, v43, vcc
	v_lshlrev_b32_e32 v42, 2, v42
	ds_bpermute_b32 v42, v42, v41
	s_waitcnt lgkmcnt(0)
	v_add_f32_e32 v41, v41, v42
	v_fmamk_f32 v41, v41, 0x3a800000, v194
	v_cmp_gt_f32_e32 vcc, s33, v41
	v_mul_f32_e32 v42, 0x4b800000, v41
	s_nop 0
	v_cndmask_b32_e32 v41, v41, v42, vcc
	v_rsq_f32_e32 v41, v41
	s_nop 0
	v_mul_f32_e32 v42, 0x45800000, v41
	v_cndmask_b32_e32 v44, v41, v42, vcc
	v_ashrrev_i32_e32 v41, 31, v40
	v_pk_mul_f32 v[50:51], v[24:25], v[44:45] op_sel_hi:[1,0]
	v_lshlrev_b64 v[42:43], 11, v[40:41]
	s_waitcnt vmcnt(3)
	v_pk_mul_f32 v[46:47], v[46:47], v[50:51]
	v_pk_mul_f32 v[50:51], v[26:27], v[44:45] op_sel_hi:[1,0]
	v_lshl_add_u64 v[42:43], s[42:43], 0, v[42:43]
	v_pk_mul_f32 v[48:49], v[48:49], v[50:51]
	v_cvt_pk_bf16_f32 v46, v46, v47
	v_cvt_pk_bf16_f32 v47, v48, v49
	v_lshl_add_u64 v[48:49], v[42:43], 0, v[140:141]
	global_store_dwordx2 v[48:49], v[46:47], off
	v_pk_mul_f32 v[50:51], v[28:29], v[44:45] op_sel_hi:[1,0]
	s_waitcnt vmcnt(3)
	v_pk_mul_f32 v[46:47], v[144:145], v[50:51]
	v_pk_mul_f32 v[50:51], v[30:31], v[44:45] op_sel_hi:[1,0]
	v_cvt_pk_bf16_f32 v46, v46, v47
	v_pk_mul_f32 v[48:49], v[146:147], v[50:51]
	v_pk_mul_f32 v[50:51], v[32:33], v[44:45] op_sel_hi:[1,0]
	v_cvt_pk_bf16_f32 v47, v48, v49
	v_lshl_add_u64 v[48:49], v[42:43], 0, v[90:91]
	global_store_dwordx2 v[48:49], v[46:47], off
	s_waitcnt vmcnt(3)
	v_pk_mul_f32 v[46:47], v[50:51], v[148:149]
	v_pk_mul_f32 v[50:51], v[34:35], v[44:45] op_sel_hi:[1,0]
	v_cvt_pk_bf16_f32 v46, v46, v47
	v_pk_mul_f32 v[48:49], v[50:51], v[150:151]
	v_pk_mul_f32 v[50:51], v[36:37], v[44:45] op_sel_hi:[1,0]
	v_cvt_pk_bf16_f32 v47, v48, v49
	v_lshl_add_u64 v[48:49], v[42:43], 0, v[92:93]
	global_store_dwordx2 v[48:49], v[46:47], off
	v_pk_mul_f32 v[44:45], v[38:39], v[44:45] op_sel_hi:[1,0]
	v_lshl_add_u64 v[42:43], v[42:43], 0, v[94:95]
	s_waitcnt vmcnt(3)
	v_pk_mul_f32 v[46:47], v[50:51], v[152:153]
	v_pk_mul_f32 v[44:45], v[44:45], v[154:155]
	v_cvt_pk_bf16_f32 v46, v46, v47
	v_cvt_pk_bf16_f32 v47, v44, v45
	global_store_dwordx2 v[42:43], v[46:47], off
